# gate scans: denormal and infinity guards around v_log_f32 removed where the argument is 1 + 2^(-|x|) in (1,2] (bit-exact)
# speedup vs baseline: 1.0063x; 1.0026x over previous
; #define LAS __attribute__((address_space(3)))
; DI void gla_a_phase(const Args& a, LAS unsigned char* lds, int vcu, int G, int tid, int lane, int wave) {
;     ...
;         { const int dk = tid & 127, sg = tid >> 7; float s = 0.f;
;             if (h != hcur) { hcur = h; bias = ba_[h * 128 + dk];
; #pragma unroll
;                 for (int r = 0; r < 16; ++r) wcol[r] = wa2_[r * 512 + h * 128 + dk]; }
; #pragma unroll 4
;             for (int t = 0; t < 16; ++t) { const LAS f32x4* gp = (const LAS f32x4*)(gas + (sg * 16 + t) * 16); const f32x4 g0 = gp[0], g1 = gp[1], g2 = gp[2], g3 = gp[3];
;                 float x = bias + ((g0.x * wcol[0] + g0.y * wcol[1]) + (g0.z * wcol[2] + g0.w * wcol[3])) + ((g1.x * wcol[4] + g1.y * wcol[5]) + (g1.z * wcol[6] + g1.w * wcol[7]))
;                                + ((g2.x * wcol[8] + g2.y * wcol[9]) + (g2.z * wcol[10] + g2.w * wcol[11])) + ((g3.x * wcol[12] + g3.y * wcol[13]) + (g3.z * wcol[14] + g3.w * wcol[15]));
;                 s += (fminf(x, 0.f) - __logf(1.f + __expf(-fabsf(x)))) * (1.f / 16.f); bt[(sg * 16 + t) * 128 + dk] = s; }
.LBB0_677:
	v_add_u32_e32 v27, 0, v25
	v_add_u32_e32 v28, 0x12000, v27
	v_add_u32_e32 v32, 0x12010, v27
	v_add_u32_e32 v36, 0x12020, v27
	v_add_u32_e32 v40, 0x12030, v27
	ds_read_b128 v[28:31], v28
	ds_read_b128 v[32:35], v32
	ds_read_b128 v[36:39], v36
	ds_read_b128 v[40:43], v40
	v_add_u32_e32 v46, 0, v26
	s_waitcnt lgkmcnt(3)
	v_mov_b32_e32 v44, v29
	v_mov_b32_e32 v29, v31
	v_mov_b32_e32 v45, v30
	s_waitcnt lgkmcnt(2)
	v_mov_b32_e32 v30, v33
	v_mov_b32_e32 v33, v35
	v_pk_mul_f32 v[28:29], v[22:23], v[28:29]
	v_mov_b32_e32 v31, v34
	v_pk_mul_f32 v[32:33], v[18:19], v[32:33]
	v_pk_fma_f32 v[28:29], v[20:21], v[44:45], v[28:29]
	v_add_u32_e32 v26, 0x800, v26
	v_add_u32_e32 v47, 0x12040, v27
	v_add_u32_e32 v114, 0x12050, v27
	v_add_u32_e32 v115, 0x12060, v27
	v_add_u32_e32 v116, 0x12070, v27
	v_add_u32_e32 v117, 0x12080, v27
	v_add_u32_e32 v118, 0x12090, v27
	v_add_u32_e32 v119, 0x120a0, v27
	v_add_u32_e32 v120, 0x120b0, v27
	v_add_u32_e32 v121, 0x120c0, v27
	v_add_u32_e32 v122, 0x120d0, v27
	v_add_u32_e32 v123, 0x120e0, v27
	v_add_u32_e32 v124, 0x120f0, v27
	s_waitcnt vmcnt(2) lgkmcnt(0)
	v_mul_f32_e32 v41, v13, v41
	v_mov_b32_e32 v27, v40
	v_mul_f32_e32 v34, v91, v37
	v_mul_f32_e32 v40, v93, v39
	v_pk_fma_f32 v[30:31], v[16:17], v[30:31], v[32:33]
	v_pk_add_f32 v[28:29], v[28:29], v[28:29] op_sel:[0,1] op_sel_hi:[1,0]
	s_waitcnt vmcnt(1)
	v_mul_f32_e32 v125, v14, v42
	s_waitcnt vmcnt(0)
	v_mul_f32_e32 v126, v15, v43
	v_pk_mul_f32 v[42:43], v[88:89], v[26:27]
	v_pk_fma_f32 v[34:35], v[90:91], v[36:37], v[34:35] op_sel_hi:[1,1,0]
	v_pk_fma_f32 v[36:37], v[92:93], v[38:39], v[40:41] op_sel_hi:[1,1,0]
	v_pk_add_f32 v[30:31], v[30:31], v[30:31] op_sel:[0,1] op_sel_hi:[1,0]
	v_pk_add_f32 v[28:29], v[88:89], v[28:29]
	v_mov_b32_e32 v35, v125
	v_mov_b32_e32 v37, v126
	v_mov_b32_e32 v31, v41
	v_mov_b32_e32 v29, v43
	v_pk_add_f32 v[32:33], v[34:35], v[36:37]
	v_pk_add_f32 v[28:29], v[28:29], v[30:31]
	s_add_i32 s13, s13, -4
	v_pk_add_f32 v[28:29], v[28:29], v[32:33]
	v_add_u32_e32 v25, 0x100, v25
	v_add_f32_e32 v27, v28, v29
	v_min_f32_e32 v28, 0, v27
	v_mul_f32_e64 v27, |v27|, s21
	v_exp_f32_e32 v27, v27
	s_cmp_eq_u32 s13, 0
	v_add_f32_e32 v27, 1.0, v27
	v_log_f32_e32 v27, v27
	s_nop 0
	v_mul_f32_e32 v30, 0x3f317217, v27
	v_fma_f32 v30, v27, s23, -v30
	v_fmac_f32_e32 v30, 0x3377d1cf, v27
	v_fmac_f32_e32 v30, 0x3f317217, v27
	v_mov_b32_e32 v27, v30
	v_sub_f32_e32 v27, v28, v27
	v_fmac_f32_e32 v24, 0x3d800000, v27
	ds_write_b32 v46, v24
	ds_read_b128 v[28:31], v47
	ds_read_b128 v[32:35], v114
	ds_read_b128 v[36:39], v115
	ds_read_b128 v[40:43], v116
	s_waitcnt lgkmcnt(3)
	v_mov_b32_e32 v44, v29
	v_mov_b32_e32 v29, v31
	v_mov_b32_e32 v45, v30
	s_waitcnt lgkmcnt(2)
	v_mov_b32_e32 v30, v33
	v_mov_b32_e32 v33, v35
	v_pk_mul_f32 v[28:29], v[22:23], v[28:29]
	v_mov_b32_e32 v31, v34
	v_pk_mul_f32 v[32:33], v[18:19], v[32:33]
	v_pk_fma_f32 v[28:29], v[20:21], v[44:45], v[28:29]
	s_waitcnt lgkmcnt(0)
	v_mul_f32_e32 v41, v13, v41
	v_mov_b32_e32 v27, v40
	v_mul_f32_e32 v34, v91, v37
	v_mul_f32_e32 v40, v93, v39
	v_pk_fma_f32 v[30:31], v[16:17], v[30:31], v[32:33]
	v_pk_add_f32 v[28:29], v[28:29], v[28:29] op_sel:[0,1] op_sel_hi:[1,0]
	v_mul_f32_e32 v47, v14, v42
	v_mul_f32_e32 v114, v15, v43
	v_pk_mul_f32 v[42:43], v[88:89], v[26:27]
	v_pk_fma_f32 v[34:35], v[90:91], v[36:37], v[34:35] op_sel_hi:[1,1,0]
	v_pk_fma_f32 v[36:37], v[92:93], v[38:39], v[40:41] op_sel_hi:[1,1,0]
	v_pk_add_f32 v[30:31], v[30:31], v[30:31] op_sel:[0,1] op_sel_hi:[1,0]
	v_pk_add_f32 v[28:29], v[88:89], v[28:29]
	v_mov_b32_e32 v35, v47
	v_mov_b32_e32 v37, v114
	v_mov_b32_e32 v31, v41
	v_mov_b32_e32 v29, v43
	v_pk_add_f32 v[32:33], v[34:35], v[36:37]
	v_pk_add_f32 v[28:29], v[28:29], v[30:31]
	s_nop 0
	v_pk_add_f32 v[28:29], v[28:29], v[32:33]
	s_nop 0
	v_add_f32_e32 v27, v28, v29
	v_min_f32_e32 v28, 0, v27
	v_mul_f32_e64 v27, |v27|, s21
	v_exp_f32_e32 v27, v27
	s_nop 0
	v_add_f32_e32 v27, 1.0, v27
	v_log_f32_e32 v27, v27
	s_nop 0
	v_mul_f32_e32 v30, 0x3f317217, v27
	v_fma_f32 v30, v27, s23, -v30
	v_fmac_f32_e32 v30, 0x3377d1cf, v27
	v_fmac_f32_e32 v30, 0x3f317217, v27
	v_mov_b32_e32 v27, v30
	v_sub_f32_e32 v27, v28, v27
	v_fmac_f32_e32 v24, 0x3d800000, v27
	ds_write_b32 v46, v24 offset:512
	ds_read_b128 v[28:31], v117
	ds_read_b128 v[32:35], v118
	ds_read_b128 v[36:39], v119
	ds_read_b128 v[40:43], v120
	s_waitcnt lgkmcnt(3)
; #define LAS __attribute__((address_space(3)))
; DI void gla_a_phase(const Args& a, LAS unsigned char* lds, int vcu, int G, int tid, int lane, int wave) {
;     ...
; #pragma unroll 4
;             for (int t = 0; t < 16; ++t) { const LAS f32x4* gp = (const LAS f32x4*)(gas + (sg * 16 + t) * 16); const f32x4 g0 = gp[0], g1 = gp[1], g2 = gp[2], g3 = gp[3];
;                 float x = bias + ((g0.x * wcol[0] + g0.y * wcol[1]) + (g0.z * wcol[2] + g0.w * wcol[3])) + ((g1.x * wcol[4] + g1.y * wcol[5]) + (g1.z * wcol[6] + g1.w * wcol[7]))
;                                + ((g2.x * wcol[8] + g2.y * wcol[9]) + (g2.z * wcol[10] + g2.w * wcol[11])) + ((g3.x * wcol[12] + g3.y * wcol[13]) + (g3.z * wcol[14] + g3.w * wcol[15]));
;                 s += (fminf(x, 0.f) - __logf(1.f + __expf(-fabsf(x)))) * (1.f / 16.f); bt[(sg * 16 + t) * 128 + dk] = s; }
;             __syncthreads();
;             float off = 0.f;
; #pragma unroll
;             for (int q = 0; q < 3; ++q) if (q < sg) off += bt[(q * 16 + 15) * 128 + dk];
	v_mov_b32_e32 v44, v29
	v_mov_b32_e32 v29, v31
	v_mov_b32_e32 v45, v30
	s_waitcnt lgkmcnt(2)
	v_mov_b32_e32 v30, v33
	v_mov_b32_e32 v33, v35
	v_pk_mul_f32 v[28:29], v[22:23], v[28:29]
	v_mov_b32_e32 v31, v34
	v_pk_mul_f32 v[32:33], v[18:19], v[32:33]
	v_pk_fma_f32 v[28:29], v[20:21], v[44:45], v[28:29]
	s_waitcnt lgkmcnt(0)
	v_mul_f32_e32 v41, v13, v41
	v_mov_b32_e32 v27, v40
	v_mul_f32_e32 v34, v91, v37
	v_mul_f32_e32 v40, v93, v39
	v_pk_fma_f32 v[30:31], v[16:17], v[30:31], v[32:33]
	v_pk_add_f32 v[28:29], v[28:29], v[28:29] op_sel:[0,1] op_sel_hi:[1,0]
	v_mul_f32_e32 v47, v14, v42
	v_mul_f32_e32 v114, v15, v43
	v_pk_mul_f32 v[42:43], v[88:89], v[26:27]
	v_pk_fma_f32 v[34:35], v[90:91], v[36:37], v[34:35] op_sel_hi:[1,1,0]
	v_pk_fma_f32 v[36:37], v[92:93], v[38:39], v[40:41] op_sel_hi:[1,1,0]
	v_pk_add_f32 v[30:31], v[30:31], v[30:31] op_sel:[0,1] op_sel_hi:[1,0]
	v_pk_add_f32 v[28:29], v[88:89], v[28:29]
	v_mov_b32_e32 v35, v47
	v_mov_b32_e32 v37, v114
	v_mov_b32_e32 v31, v41
	v_mov_b32_e32 v29, v43
	v_pk_add_f32 v[32:33], v[34:35], v[36:37]
	v_pk_add_f32 v[28:29], v[28:29], v[30:31]
	s_nop 0
	v_pk_add_f32 v[28:29], v[28:29], v[32:33]
	s_nop 0
	v_add_f32_e32 v27, v28, v29
	v_min_f32_e32 v28, 0, v27
	v_mul_f32_e64 v27, |v27|, s21
	v_exp_f32_e32 v27, v27
	s_nop 0
	v_add_f32_e32 v27, 1.0, v27
	v_log_f32_e32 v27, v27
	s_nop 0
	v_mul_f32_e32 v30, 0x3f317217, v27
	v_fma_f32 v30, v27, s23, -v30
	v_fmac_f32_e32 v30, 0x3377d1cf, v27
	v_fmac_f32_e32 v30, 0x3f317217, v27
	v_mov_b32_e32 v27, v30
	v_sub_f32_e32 v27, v28, v27
	v_fmac_f32_e32 v24, 0x3d800000, v27
	ds_write_b32 v46, v24 offset:1024
	ds_read_b128 v[28:31], v121
	ds_read_b128 v[32:35], v122
	ds_read_b128 v[36:39], v123
	ds_read_b128 v[40:43], v124
	s_waitcnt lgkmcnt(3)
	v_mov_b32_e32 v44, v29
	v_mov_b32_e32 v29, v31
	v_mov_b32_e32 v45, v30
	s_waitcnt lgkmcnt(2)
	v_mov_b32_e32 v30, v33
	v_mov_b32_e32 v33, v35
	v_pk_mul_f32 v[28:29], v[22:23], v[28:29]
	v_mov_b32_e32 v31, v34
	v_pk_mul_f32 v[32:33], v[18:19], v[32:33]
	v_pk_fma_f32 v[28:29], v[20:21], v[44:45], v[28:29]
	s_waitcnt lgkmcnt(0)
	v_mul_f32_e32 v41, v13, v41
	v_mov_b32_e32 v27, v40
	v_mul_f32_e32 v34, v91, v37
	v_mul_f32_e32 v40, v93, v39
	v_pk_fma_f32 v[30:31], v[16:17], v[30:31], v[32:33]
	v_pk_add_f32 v[28:29], v[28:29], v[28:29] op_sel:[0,1] op_sel_hi:[1,0]
	v_mul_f32_e32 v47, v14, v42
	v_mul_f32_e32 v114, v15, v43
	v_pk_mul_f32 v[42:43], v[88:89], v[26:27]
	v_pk_fma_f32 v[34:35], v[90:91], v[36:37], v[34:35] op_sel_hi:[1,1,0]
	v_pk_fma_f32 v[36:37], v[92:93], v[38:39], v[40:41] op_sel_hi:[1,1,0]
	v_pk_add_f32 v[30:31], v[30:31], v[30:31] op_sel:[0,1] op_sel_hi:[1,0]
	v_pk_add_f32 v[28:29], v[88:89], v[28:29]
	v_mov_b32_e32 v35, v47
	v_mov_b32_e32 v37, v114
	v_mov_b32_e32 v31, v41
	v_mov_b32_e32 v29, v43
	v_pk_add_f32 v[32:33], v[34:35], v[36:37]
	v_pk_add_f32 v[28:29], v[28:29], v[30:31]
	s_nop 0
	v_pk_add_f32 v[28:29], v[28:29], v[32:33]
	s_nop 0
	v_add_f32_e32 v27, v28, v29
	v_mul_f32_e64 v28, |v27|, s21
	v_exp_f32_e32 v28, v28
	v_min_f32_e32 v27, 0, v27
	v_add_f32_e32 v28, 1.0, v28
	v_log_f32_e32 v28, v28
	s_nop 0
	v_mul_f32_e32 v30, 0x3f317217, v28
	v_fma_f32 v30, v28, s23, -v30
	v_fmac_f32_e32 v30, 0x3377d1cf, v28
	v_fmac_f32_e32 v30, 0x3f317217, v28
	v_mov_b32_e32 v28, v30
	v_sub_f32_e32 v27, v27, v28
	v_fmac_f32_e32 v24, 0x3d800000, v27
	ds_write_b32 v46, v24 offset:1536
	s_cbranch_scc0 .LBB0_677
	v_mov_b32_e32 v16, 0
	s_waitcnt lgkmcnt(0)
	s_barrier
	s_and_saveexec_b64 s[14:15], s[2:3]
	s_cbranch_execz .LBB0_684
	ds_read_b32 v16, v95
	s_waitcnt lgkmcnt(0)
	v_add_f32_e32 v16, 0, v16
	s_or_b64 exec, exec, s[14:15]
	s_and_saveexec_b64 s[14:15], s[6:7]
	s_cbranch_execnz .LBB0_685

; #define LAS __attribute__((address_space(3)))
; DI void gla_c_phase(const Args& a, LAS unsigned char* lds, int vcu, int G, int tid, int lane, int wave) {
;     ...
;         { const int dk = tid & 127, sg = tid >> 7; float s = 0.f;
;             if (h != hcur) { hcur = h; bias = ba_[h * 128 + dk];
; #pragma unroll
;                 for (int r = 0; r < 16; ++r) wcol[r] = wa2_[r * 512 + h * 128 + dk]; }
; #pragma unroll 4
;             for (int t = 0; t < 16; ++t) { const LAS f32x4* gp = (const LAS f32x4*)(gas + (sg * 16 + t) * 16); const f32x4 g0 = gp[0], g1 = gp[1], g2 = gp[2], g3 = gp[3];
;                 float x = bias + ((g0.x * wcol[0] + g0.y * wcol[1]) + (g0.z * wcol[2] + g0.w * wcol[3])) + ((g1.x * wcol[4] + g1.y * wcol[5]) + (g1.z * wcol[6] + g1.w * wcol[7]))
;                                + ((g2.x * wcol[8] + g2.y * wcol[9]) + (g2.z * wcol[10] + g2.w * wcol[11])) + ((g3.x * wcol[12] + g3.y * wcol[13]) + (g3.z * wcol[14] + g3.w * wcol[15]));
;                 s += (fminf(x, 0.f) - __logf(1.f + __expf(-fabsf(x)))) * (1.f / 16.f); bt[(sg * 16 + t) * 128 + dk] = s; }
.LBB0_869:
	v_add_u32_e32 v27, 0, v25
	v_add_u32_e32 v28, 0x1fc00, v27
	v_add_u32_e32 v32, 0x1fc10, v27
	v_add_u32_e32 v36, 0x1fc20, v27
	v_add_u32_e32 v40, 0x1fc30, v27
	ds_read_b128 v[28:31], v28
	ds_read_b128 v[32:35], v32
	ds_read_b128 v[36:39], v36
	ds_read_b128 v[40:43], v40
	v_add_u32_e32 v46, 0, v26
	s_waitcnt lgkmcnt(3)
	v_mov_b32_e32 v44, v29
	v_mov_b32_e32 v29, v31
	v_mov_b32_e32 v45, v30
	s_waitcnt lgkmcnt(2)
	v_mov_b32_e32 v30, v33
	v_mov_b32_e32 v33, v35
	v_pk_mul_f32 v[28:29], v[22:23], v[28:29]
	v_mov_b32_e32 v31, v34
	v_pk_mul_f32 v[32:33], v[18:19], v[32:33]
	v_pk_fma_f32 v[28:29], v[20:21], v[44:45], v[28:29]
	v_add_u32_e32 v26, 0x800, v26
	v_add_u32_e32 v47, 0x1fc40, v27
	v_add_u32_e32 v48, 0x1fc50, v27
	v_add_u32_e32 v49, 0x1fc60, v27
	v_add_u32_e32 v50, 0x1fc70, v27
	v_add_u32_e32 v51, 0x1fc80, v27
	v_add_u32_e32 v52, 0x1fc90, v27
	v_add_u32_e32 v53, 0x1fca0, v27
	v_add_u32_e32 v54, 0x1fcb0, v27
	v_add_u32_e32 v55, 0x1fcc0, v27
	v_add_u32_e32 v56, 0x1fcd0, v27
	v_add_u32_e32 v57, 0x1fce0, v27
	v_add_u32_e32 v58, 0x1fcf0, v27
	s_waitcnt vmcnt(2) lgkmcnt(0)
	v_mul_f32_e32 v41, v13, v41
	v_mov_b32_e32 v27, v40
	v_mul_f32_e32 v34, v101, v37
	v_mul_f32_e32 v40, v103, v39
	v_pk_fma_f32 v[30:31], v[16:17], v[30:31], v[32:33]
	v_pk_add_f32 v[28:29], v[28:29], v[28:29] op_sel:[0,1] op_sel_hi:[1,0]
	s_waitcnt vmcnt(1)
	v_mul_f32_e32 v59, v14, v42
	s_waitcnt vmcnt(0)
	v_mul_f32_e32 v60, v15, v43
	v_pk_mul_f32 v[42:43], v[98:99], v[26:27]
	v_pk_fma_f32 v[34:35], v[100:101], v[36:37], v[34:35] op_sel_hi:[1,1,0]
	v_pk_fma_f32 v[36:37], v[102:103], v[38:39], v[40:41] op_sel_hi:[1,1,0]
	v_pk_add_f32 v[30:31], v[30:31], v[30:31] op_sel:[0,1] op_sel_hi:[1,0]
	v_pk_add_f32 v[28:29], v[98:99], v[28:29]
	v_mov_b32_e32 v35, v59
	v_mov_b32_e32 v37, v60
	v_mov_b32_e32 v31, v41
	v_mov_b32_e32 v29, v43
	v_pk_add_f32 v[32:33], v[34:35], v[36:37]
	v_pk_add_f32 v[28:29], v[28:29], v[30:31]
	s_add_i32 s52, s52, -4
	v_pk_add_f32 v[28:29], v[28:29], v[32:33]
	v_add_u32_e32 v25, 0x100, v25
	v_add_f32_e32 v27, v28, v29
	v_min_f32_e32 v28, 0, v27
	v_mul_f32_e64 v27, |v27|, s77
	v_exp_f32_e32 v27, v27
	s_cmp_eq_u32 s52, 0
	v_add_f32_e32 v27, 1.0, v27
	v_log_f32_e32 v27, v27
	s_nop 0
	v_mul_f32_e32 v30, 0x3f317217, v27
	v_fma_f32 v30, v27, s71, -v30
	v_fmac_f32_e32 v30, 0x3377d1cf, v27
	v_fmac_f32_e32 v30, 0x3f317217, v27
	v_mov_b32_e32 v27, v30
	v_sub_f32_e32 v27, v28, v27
	v_fmac_f32_e32 v24, 0x3d800000, v27
	ds_write_b32 v46, v24
	ds_read_b128 v[28:31], v47
	ds_read_b128 v[32:35], v48
	ds_read_b128 v[36:39], v49
	ds_read_b128 v[40:43], v50
	s_waitcnt lgkmcnt(3)
	v_mov_b32_e32 v44, v29
	v_mov_b32_e32 v29, v31
	v_mov_b32_e32 v45, v30
	s_waitcnt lgkmcnt(2)
	v_mov_b32_e32 v30, v33
	v_mov_b32_e32 v33, v35
	v_pk_mul_f32 v[28:29], v[22:23], v[28:29]
	v_mov_b32_e32 v31, v34
	v_pk_mul_f32 v[32:33], v[18:19], v[32:33]
	v_pk_fma_f32 v[28:29], v[20:21], v[44:45], v[28:29]
	s_waitcnt lgkmcnt(0)
	v_mul_f32_e32 v41, v13, v41
	v_mov_b32_e32 v27, v40
	v_mul_f32_e32 v34, v101, v37
	v_mul_f32_e32 v40, v103, v39
	v_pk_fma_f32 v[30:31], v[16:17], v[30:31], v[32:33]
	v_pk_add_f32 v[28:29], v[28:29], v[28:29] op_sel:[0,1] op_sel_hi:[1,0]
	v_mul_f32_e32 v47, v14, v42
	v_mul_f32_e32 v48, v15, v43
	v_pk_mul_f32 v[42:43], v[98:99], v[26:27]
	v_pk_fma_f32 v[34:35], v[100:101], v[36:37], v[34:35] op_sel_hi:[1,1,0]
	v_pk_fma_f32 v[36:37], v[102:103], v[38:39], v[40:41] op_sel_hi:[1,1,0]
	v_pk_add_f32 v[30:31], v[30:31], v[30:31] op_sel:[0,1] op_sel_hi:[1,0]
	v_pk_add_f32 v[28:29], v[98:99], v[28:29]
	v_mov_b32_e32 v35, v47
	v_mov_b32_e32 v37, v48
	v_mov_b32_e32 v31, v41
	v_mov_b32_e32 v29, v43
	v_pk_add_f32 v[32:33], v[34:35], v[36:37]
	v_pk_add_f32 v[28:29], v[28:29], v[30:31]
	s_nop 0
	v_pk_add_f32 v[28:29], v[28:29], v[32:33]
	s_nop 0
	v_add_f32_e32 v27, v28, v29
	v_min_f32_e32 v28, 0, v27
	v_mul_f32_e64 v27, |v27|, s77
	v_exp_f32_e32 v27, v27
	s_nop 0
	v_add_f32_e32 v27, 1.0, v27
	v_log_f32_e32 v27, v27
	s_nop 0
	v_mul_f32_e32 v30, 0x3f317217, v27
	v_fma_f32 v30, v27, s71, -v30
	v_fmac_f32_e32 v30, 0x3377d1cf, v27
	v_fmac_f32_e32 v30, 0x3f317217, v27
	v_mov_b32_e32 v27, v30
	v_sub_f32_e32 v27, v28, v27
	v_fmac_f32_e32 v24, 0x3d800000, v27
	ds_write_b32 v46, v24 offset:512
	ds_read_b128 v[28:31], v51
	ds_read_b128 v[32:35], v52
	ds_read_b128 v[36:39], v53
	ds_read_b128 v[40:43], v54
	s_waitcnt lgkmcnt(3)
; #define LAS __attribute__((address_space(3)))
; DI void gla_c_phase(const Args& a, LAS unsigned char* lds, int vcu, int G, int tid, int lane, int wave) {
;     ...
; #pragma unroll 4
;             for (int t = 0; t < 16; ++t) { const LAS f32x4* gp = (const LAS f32x4*)(gas + (sg * 16 + t) * 16); const f32x4 g0 = gp[0], g1 = gp[1], g2 = gp[2], g3 = gp[3];
;                 float x = bias + ((g0.x * wcol[0] + g0.y * wcol[1]) + (g0.z * wcol[2] + g0.w * wcol[3])) + ((g1.x * wcol[4] + g1.y * wcol[5]) + (g1.z * wcol[6] + g1.w * wcol[7]))
;                                + ((g2.x * wcol[8] + g2.y * wcol[9]) + (g2.z * wcol[10] + g2.w * wcol[11])) + ((g3.x * wcol[12] + g3.y * wcol[13]) + (g3.z * wcol[14] + g3.w * wcol[15]));
;                 s += (fminf(x, 0.f) - __logf(1.f + __expf(-fabsf(x)))) * (1.f / 16.f); bt[(sg * 16 + t) * 128 + dk] = s; }
;             __syncthreads();
;             float off = 0.f;
; #pragma unroll
;             for (int q = 0; q < 3; ++q) if (q < sg) off += bt[(q * 16 + 15) * 128 + dk];
	v_mov_b32_e32 v44, v29
	v_mov_b32_e32 v29, v31
	v_mov_b32_e32 v45, v30
	s_waitcnt lgkmcnt(2)
	v_mov_b32_e32 v30, v33
	v_mov_b32_e32 v33, v35
	v_pk_mul_f32 v[28:29], v[22:23], v[28:29]
	v_mov_b32_e32 v31, v34
	v_pk_mul_f32 v[32:33], v[18:19], v[32:33]
	v_pk_fma_f32 v[28:29], v[20:21], v[44:45], v[28:29]
	s_waitcnt lgkmcnt(0)
	v_mul_f32_e32 v41, v13, v41
	v_mov_b32_e32 v27, v40
	v_mul_f32_e32 v34, v101, v37
	v_mul_f32_e32 v40, v103, v39
	v_pk_fma_f32 v[30:31], v[16:17], v[30:31], v[32:33]
	v_pk_add_f32 v[28:29], v[28:29], v[28:29] op_sel:[0,1] op_sel_hi:[1,0]
	v_mul_f32_e32 v47, v14, v42
	v_mul_f32_e32 v48, v15, v43
	v_pk_mul_f32 v[42:43], v[98:99], v[26:27]
	v_pk_fma_f32 v[34:35], v[100:101], v[36:37], v[34:35] op_sel_hi:[1,1,0]
	v_pk_fma_f32 v[36:37], v[102:103], v[38:39], v[40:41] op_sel_hi:[1,1,0]
	v_pk_add_f32 v[30:31], v[30:31], v[30:31] op_sel:[0,1] op_sel_hi:[1,0]
	v_pk_add_f32 v[28:29], v[98:99], v[28:29]
	v_mov_b32_e32 v35, v47
	v_mov_b32_e32 v37, v48
	v_mov_b32_e32 v31, v41
	v_mov_b32_e32 v29, v43
	v_pk_add_f32 v[32:33], v[34:35], v[36:37]
	v_pk_add_f32 v[28:29], v[28:29], v[30:31]
	s_nop 0
	v_pk_add_f32 v[28:29], v[28:29], v[32:33]
	s_nop 0
	v_add_f32_e32 v27, v28, v29
	v_min_f32_e32 v28, 0, v27
	v_mul_f32_e64 v27, |v27|, s77
	v_exp_f32_e32 v27, v27
	s_nop 0
	v_add_f32_e32 v27, 1.0, v27
	v_log_f32_e32 v27, v27
	s_nop 0
	v_mul_f32_e32 v30, 0x3f317217, v27
	v_fma_f32 v30, v27, s71, -v30
	v_fmac_f32_e32 v30, 0x3377d1cf, v27
	v_fmac_f32_e32 v30, 0x3f317217, v27
	v_mov_b32_e32 v27, v30
	v_sub_f32_e32 v27, v28, v27
	v_fmac_f32_e32 v24, 0x3d800000, v27
	ds_write_b32 v46, v24 offset:1024
	ds_read_b128 v[28:31], v55
	ds_read_b128 v[32:35], v56
	ds_read_b128 v[36:39], v57
	ds_read_b128 v[40:43], v58
	s_waitcnt lgkmcnt(3)
	v_mov_b32_e32 v44, v29
	v_mov_b32_e32 v29, v31
	v_mov_b32_e32 v45, v30
	s_waitcnt lgkmcnt(2)
	v_mov_b32_e32 v30, v33
	v_mov_b32_e32 v33, v35
	v_pk_mul_f32 v[28:29], v[22:23], v[28:29]
	v_mov_b32_e32 v31, v34
	v_pk_mul_f32 v[32:33], v[18:19], v[32:33]
	v_pk_fma_f32 v[28:29], v[20:21], v[44:45], v[28:29]
	s_waitcnt lgkmcnt(0)
	v_mul_f32_e32 v41, v13, v41
	v_mov_b32_e32 v27, v40
	v_mul_f32_e32 v34, v101, v37
	v_mul_f32_e32 v40, v103, v39
	v_pk_fma_f32 v[30:31], v[16:17], v[30:31], v[32:33]
	v_pk_add_f32 v[28:29], v[28:29], v[28:29] op_sel:[0,1] op_sel_hi:[1,0]
	v_mul_f32_e32 v47, v14, v42
	v_mul_f32_e32 v48, v15, v43
	v_pk_mul_f32 v[42:43], v[98:99], v[26:27]
	v_pk_fma_f32 v[34:35], v[100:101], v[36:37], v[34:35] op_sel_hi:[1,1,0]
	v_pk_fma_f32 v[36:37], v[102:103], v[38:39], v[40:41] op_sel_hi:[1,1,0]
	v_pk_add_f32 v[30:31], v[30:31], v[30:31] op_sel:[0,1] op_sel_hi:[1,0]
	v_pk_add_f32 v[28:29], v[98:99], v[28:29]
	v_mov_b32_e32 v35, v47
	v_mov_b32_e32 v37, v48
	v_mov_b32_e32 v31, v41
	v_mov_b32_e32 v29, v43
	v_pk_add_f32 v[32:33], v[34:35], v[36:37]
	v_pk_add_f32 v[28:29], v[28:29], v[30:31]
	s_nop 0
	v_pk_add_f32 v[28:29], v[28:29], v[32:33]
	s_nop 0
	v_add_f32_e32 v27, v28, v29
	v_mul_f32_e64 v28, |v27|, s77
	v_exp_f32_e32 v28, v28
	v_min_f32_e32 v27, 0, v27
	v_add_f32_e32 v28, 1.0, v28
	v_log_f32_e32 v28, v28
	s_nop 0
	v_mul_f32_e32 v30, 0x3f317217, v28
	v_fma_f32 v30, v28, s71, -v30
	v_fmac_f32_e32 v30, 0x3377d1cf, v28
	v_fmac_f32_e32 v30, 0x3f317217, v28
	v_mov_b32_e32 v28, v30
	v_sub_f32_e32 v27, v27, v28
	v_fmac_f32_e32 v24, 0x3d800000, v27
	ds_write_b32 v46, v24 offset:1536
	s_cbranch_scc0 .LBB0_869
	v_mov_b32_e32 v16, 0
	s_waitcnt lgkmcnt(0)
	s_barrier
	s_and_saveexec_b64 s[62:63], s[6:7]
	s_cbranch_execz .LBB0_880
	ds_read_b32 v16, v111
	s_waitcnt lgkmcnt(0)
	v_add_f32_e32 v16, 0, v16
	s_or_b64 exec, exec, s[62:63]
	s_and_saveexec_b64 s[62:63], s[2:3]
	s_cbranch_execnz .LBB0_881
